# GEMM1 units: accumulator zeroing (128 v_mov per wave and unit) replaced by C=0 first-touch MFMAs in a straight-line copy of the first two K phases; on top of convpipe+sched
# baseline (speedup 1.0000x reference)
.LBB0_288:
	s_ashr_i32 s53, s52, 31
	s_lshl_b64 s[54:55], s[52:53], 19
	s_add_u32 s54, s66, s54
	s_addc_u32 s55, s67, s55
	s_and_b64 s[56:57], s[40:41], exec
	s_cselect_b32 s53, s55, s61
	s_cselect_b32 s80, s54, s60
	s_ashr_i32 s43, s42, 31
	s_lshl_b64 s[56:57], s[42:43], 19
	s_add_u32 s56, s68, s56
	s_addc_u32 s57, s69, s57
	s_and_b64 s[62:63], s[40:41], exec
	s_cselect_b32 s43, s57, s59
	s_cselect_b32 s81, s56, s58
	s_add_u32 s82, s58, 0x100
	s_addc_u32 s83, s59, 0
	s_add_u32 s58, s60, 0x40080
	s_addc_u32 s59, s61, 0
	s_mov_b32 s84, -2
	s_add_u32 s60, s58, 0xfffc0080
	s_addc_u32 s61, s59, -1
	s_add_i32 s85, 0, 0x10000
	s_cmp_eq_u32 s84, 12
	s_cselect_b32 s63, s53, s61
	s_cselect_b32 s62, s80, s60
	v_add_u32_e32 v140, s85, v142
	s_cselect_b32 s61, s43, s83
	s_cselect_b32 s60, s81, s82
	s_add_i32 s90, 0, 0x14000
	ds_read_b128 v[156:159], v140
	ds_read_b128 v[160:163], v140 offset:1024
	ds_read_b128 v[164:167], v140 offset:2048
	ds_read_b128 v[168:171], v140 offset:3072
	v_add_u32_e32 v140, s90, v142
	ds_read_b128 v[172:175], v140
	ds_read_b128 v[176:179], v140 offset:1024
	ds_read_b128 v[180:183], v140 offset:2048
	ds_read_b128 v[184:187], v140 offset:3072
	v_lshl_add_u64 v[140:141], s[58:59], 0, v[138:139]
	s_add_i32 m0, s71, 0xc000
	ds_read_b128 v[188:191], v144
	ds_read_b128 v[192:195], v144 offset:1024
	ds_read_b128 v[196:199], v144 offset:2048
	ds_read_b128 v[200:203], v144 offset:3072
	ds_read_b128 v[204:207], v144 offset:4096
	ds_read_b128 v[218:221], v144 offset:5120
	ds_read_b128 v[222:225], v144 offset:6144
	ds_read_b128 v[226:229], v144 offset:7168
	global_load_lds_dwordx4 v[140:141], off
	v_lshl_add_u64 v[140:141], s[58:59], 0, v[136:137]
	s_add_i32 m0, s71, 0xe000
	s_nop 0
	global_load_lds_dwordx4 v[140:141], off
	s_waitcnt vmcnt(8)
	s_waitcnt lgkmcnt(0)
	s_barrier
	s_setprio 1
	s_waitcnt lgkmcnt(0)
	v_mfma_f32_16x16x32_bf16 v[124:127], v[156:159], v[188:191], 0
	v_mfma_f32_16x16x32_bf16 v[120:123], v[164:167], v[188:191], 0
	v_mfma_f32_16x16x32_bf16 v[112:115], v[156:159], v[196:199], 0
	v_mfma_f32_16x16x32_bf16 v[104:107], v[164:167], v[196:199], 0
	v_mfma_f32_16x16x32_bf16 v[96:99], v[156:159], v[204:207], 0
	v_mfma_f32_16x16x32_bf16 v[88:91], v[164:167], v[204:207], 0
	v_mfma_f32_16x16x32_bf16 v[80:83], v[156:159], v[222:225], 0
	v_mfma_f32_16x16x32_bf16 v[72:75], v[164:167], v[222:225], 0
	v_mfma_f32_16x16x32_bf16 v[124:127], v[160:163], v[192:195], v[124:127]
	v_mfma_f32_16x16x32_bf16 v[120:123], v[168:171], v[192:195], v[120:123]
	v_mfma_f32_16x16x32_bf16 v[112:115], v[160:163], v[200:203], v[112:115]
	v_mfma_f32_16x16x32_bf16 v[104:107], v[168:171], v[200:203], v[104:107]
	v_mfma_f32_16x16x32_bf16 v[96:99], v[160:163], v[218:221], v[96:99]
	v_mfma_f32_16x16x32_bf16 v[88:91], v[168:171], v[218:221], v[88:91]
	v_mfma_f32_16x16x32_bf16 v[80:83], v[160:163], v[226:229], v[80:83]
	v_mfma_f32_16x16x32_bf16 v[72:75], v[168:171], v[226:229], v[72:75]
	s_setprio 0
	s_setprio 1
	v_mfma_f32_16x16x32_bf16 v[116:119], v[172:175], v[188:191], 0
	v_mfma_f32_16x16x32_bf16 v[108:111], v[180:183], v[188:191], 0
	v_mfma_f32_16x16x32_bf16 v[100:103], v[172:175], v[196:199], 0
	v_mfma_f32_16x16x32_bf16 v[92:95], v[180:183], v[196:199], 0
	v_mfma_f32_16x16x32_bf16 v[84:87], v[172:175], v[204:207], 0
	v_mfma_f32_16x16x32_bf16 v[76:79], v[180:183], v[204:207], 0
	v_mfma_f32_16x16x32_bf16 v[68:71], v[172:175], v[222:225], 0
	v_mfma_f32_16x16x32_bf16 v[64:67], v[180:183], v[222:225], 0
	v_mfma_f32_16x16x32_bf16 v[116:119], v[176:179], v[192:195], v[116:119]
	v_mfma_f32_16x16x32_bf16 v[108:111], v[184:187], v[192:195], v[108:111]
	v_mfma_f32_16x16x32_bf16 v[100:103], v[176:179], v[200:203], v[100:103]
	v_mfma_f32_16x16x32_bf16 v[92:95], v[184:187], v[200:203], v[92:95]
	v_mfma_f32_16x16x32_bf16 v[84:87], v[176:179], v[218:221], v[84:87]
	v_mfma_f32_16x16x32_bf16 v[76:79], v[184:187], v[218:221], v[76:79]
	v_mfma_f32_16x16x32_bf16 v[68:71], v[176:179], v[226:229], v[68:71]
	v_mfma_f32_16x16x32_bf16 v[64:67], v[184:187], v[226:229], v[64:67]
	s_setprio 0
	s_barrier
	s_add_i32 s85, s85, s70
	v_lshl_add_u64 v[140:141], s[60:61], 0, v[148:149]
	s_mov_b32 m0, s85
	ds_read_b128 v[188:191], v144 offset:16384
	ds_read_b128 v[192:195], v144 offset:17408
	ds_read_b128 v[196:199], v144 offset:18432
	ds_read_b128 v[200:203], v144 offset:19456
	ds_read_b128 v[204:207], v144 offset:20480
	ds_read_b128 v[218:221], v144 offset:21504
	ds_read_b128 v[222:225], v144 offset:22528
	ds_read_b128 v[226:229], v144 offset:23552
	global_load_lds_dwordx4 v[140:141], off
	s_add_i32 m0, s85, 0x2000
	s_add_u32 s88, s60, 0x40000
	v_lshl_add_u64 v[146:147], s[60:61], 0, v[130:131]
	s_addc_u32 s89, s61, 0
	s_add_i32 s85, s90, s70
	global_load_lds_dwordx4 v[146:147], off
	v_lshl_add_u64 v[208:209], s[88:89], 0, v[148:149]
	s_mov_b32 m0, s85
	v_lshl_add_u64 v[212:213], s[62:63], 0, v[132:133]
	global_load_lds_dwordx4 v[208:209], off
	v_lshl_add_u64 v[208:209], s[88:89], 0, v[130:131]
	s_add_i32 m0, s85, 0x2000
	s_nop 0
	global_load_lds_dwordx4 v[208:209], off
	v_lshl_add_u64 v[208:209], s[62:63], 0, v[134:135]
	s_mov_b32 m0, s71
	s_nop 0
	global_load_lds_dwordx4 v[208:209], off
	s_mov_b32 m0, s72
	s_nop 0
	global_load_lds_dwordx4 v[212:213], off
	s_waitcnt vmcnt(8)
	s_waitcnt lgkmcnt(0)
	s_barrier
	s_setprio 1
	s_waitcnt lgkmcnt(0)
	v_mfma_f32_16x16x32_bf16 v[60:63], v[156:159], v[188:191], 0
	v_mfma_f32_16x16x32_bf16 v[56:59], v[164:167], v[188:191], 0
	v_mfma_f32_16x16x32_bf16 v[48:51], v[156:159], v[196:199], 0
	v_mfma_f32_16x16x32_bf16 v[40:43], v[164:167], v[196:199], 0
	v_mfma_f32_16x16x32_bf16 v[32:35], v[156:159], v[204:207], 0
	v_mfma_f32_16x16x32_bf16 v[24:27], v[164:167], v[204:207], 0
	v_mfma_f32_16x16x32_bf16 v[16:19], v[156:159], v[222:225], 0
	v_mfma_f32_16x16x32_bf16 v[8:11], v[164:167], v[222:225], 0
	v_mfma_f32_16x16x32_bf16 v[60:63], v[160:163], v[192:195], v[60:63]
	v_mfma_f32_16x16x32_bf16 v[56:59], v[168:171], v[192:195], v[56:59]
	v_mfma_f32_16x16x32_bf16 v[48:51], v[160:163], v[200:203], v[48:51]
	v_mfma_f32_16x16x32_bf16 v[40:43], v[168:171], v[200:203], v[40:43]
	v_mfma_f32_16x16x32_bf16 v[32:35], v[160:163], v[218:221], v[32:35]
	v_mfma_f32_16x16x32_bf16 v[24:27], v[168:171], v[218:221], v[24:27]
	v_mfma_f32_16x16x32_bf16 v[16:19], v[160:163], v[226:229], v[16:19]
	v_mfma_f32_16x16x32_bf16 v[8:11], v[168:171], v[226:229], v[8:11]
	s_setprio 0
	s_setprio 1
	v_mfma_f32_16x16x32_bf16 v[52:55], v[172:175], v[188:191], 0
	v_mfma_f32_16x16x32_bf16 v[44:47], v[180:183], v[188:191], 0
	v_mfma_f32_16x16x32_bf16 v[36:39], v[172:175], v[196:199], 0
	v_mfma_f32_16x16x32_bf16 v[28:31], v[180:183], v[196:199], 0
	v_mfma_f32_16x16x32_bf16 v[20:23], v[172:175], v[204:207], 0
	v_mfma_f32_16x16x32_bf16 v[12:15], v[180:183], v[204:207], 0
	v_mfma_f32_16x16x32_bf16 v[4:7], v[172:175], v[222:225], 0
	v_mfma_f32_16x16x32_bf16 v[0:3], v[180:183], v[222:225], 0
	v_mfma_f32_16x16x32_bf16 v[52:55], v[176:179], v[192:195], v[52:55]
	v_mfma_f32_16x16x32_bf16 v[44:47], v[184:187], v[192:195], v[44:47]
	v_mfma_f32_16x16x32_bf16 v[36:39], v[176:179], v[200:203], v[36:39]
	v_mfma_f32_16x16x32_bf16 v[28:31], v[184:187], v[200:203], v[28:31]
	v_mfma_f32_16x16x32_bf16 v[20:23], v[176:179], v[218:221], v[20:23]
	v_mfma_f32_16x16x32_bf16 v[12:15], v[184:187], v[218:221], v[12:15]
	v_mfma_f32_16x16x32_bf16 v[4:7], v[176:179], v[226:229], v[4:7]
	v_mfma_f32_16x16x32_bf16 v[0:3], v[184:187], v[226:229], v[0:3]
	s_setprio 0
	s_barrier
	s_branch .Lg1_p3
	.p2align 6
	.fill 12, 4, 0xBF800000

.Lg1_p3:
	s_add_i32 s85, 0, 0x18000
	v_add_u32_e32 v145, s85, v142
	s_add_i32 s88, 0, 0x1c000
	ds_read_b128 v[156:159], v145
	ds_read_b128 v[160:163], v145 offset:1024
	ds_read_b128 v[164:167], v145 offset:2048
	ds_read_b128 v[168:171], v145 offset:3072
	v_add_u32_e32 v145, s88, v142
	ds_read_b128 v[172:175], v145
	ds_read_b128 v[176:179], v145 offset:1024
	ds_read_b128 v[180:183], v145 offset:2048
	ds_read_b128 v[184:187], v145 offset:3072
	s_add_u32 s62, s62, 0x40000
	s_addc_u32 s63, s63, 0
	s_mov_b32 m0, s73
	v_lshl_add_u64 v[230:231], s[62:63], 0, v[134:135]
	ds_read_b128 v[188:191], v144 offset:32768
	ds_read_b128 v[192:195], v144 offset:33792
	ds_read_b128 v[196:199], v144 offset:34816
	ds_read_b128 v[200:203], v144 offset:35840
	ds_read_b128 v[204:207], v144 offset:36864
	ds_read_b128 v[218:221], v144 offset:37888
	ds_read_b128 v[222:225], v144 offset:38912
	ds_read_b128 v[226:229], v144 offset:39936
	global_load_lds_dwordx4 v[230:231], off
	v_lshl_add_u64 v[230:231], s[62:63], 0, v[132:133]
	s_mov_b32 m0, s74
	s_nop 0
	global_load_lds_dwordx4 v[230:231], off
	s_waitcnt vmcnt(8)
	s_waitcnt lgkmcnt(0)
	s_barrier
	s_setprio 1
	s_waitcnt lgkmcnt(0)
	v_mfma_f32_16x16x32_bf16 v[124:127], v[156:159], v[188:191], v[124:127]
	v_mfma_f32_16x16x32_bf16 v[120:123], v[164:167], v[188:191], v[120:123]
	v_mfma_f32_16x16x32_bf16 v[112:115], v[156:159], v[196:199], v[112:115]
	v_mfma_f32_16x16x32_bf16 v[104:107], v[164:167], v[196:199], v[104:107]
	v_mfma_f32_16x16x32_bf16 v[96:99], v[156:159], v[204:207], v[96:99]
	v_mfma_f32_16x16x32_bf16 v[88:91], v[164:167], v[204:207], v[88:91]
	v_mfma_f32_16x16x32_bf16 v[80:83], v[156:159], v[222:225], v[80:83]
	v_mfma_f32_16x16x32_bf16 v[72:75], v[164:167], v[222:225], v[72:75]
	v_mfma_f32_16x16x32_bf16 v[124:127], v[160:163], v[192:195], v[124:127]
	v_mfma_f32_16x16x32_bf16 v[120:123], v[168:171], v[192:195], v[120:123]
	v_mfma_f32_16x16x32_bf16 v[112:115], v[160:163], v[200:203], v[112:115]
	v_mfma_f32_16x16x32_bf16 v[104:107], v[168:171], v[200:203], v[104:107]
	v_mfma_f32_16x16x32_bf16 v[96:99], v[160:163], v[218:221], v[96:99]
	v_mfma_f32_16x16x32_bf16 v[88:91], v[168:171], v[218:221], v[88:91]
	v_mfma_f32_16x16x32_bf16 v[80:83], v[160:163], v[226:229], v[80:83]
	v_mfma_f32_16x16x32_bf16 v[72:75], v[168:171], v[226:229], v[72:75]
	s_setprio 0
	s_setprio 1
	v_mfma_f32_16x16x32_bf16 v[116:119], v[172:175], v[188:191], v[116:119]
	v_mfma_f32_16x16x32_bf16 v[108:111], v[180:183], v[188:191], v[108:111]
	v_mfma_f32_16x16x32_bf16 v[100:103], v[172:175], v[196:199], v[100:103]
	v_mfma_f32_16x16x32_bf16 v[92:95], v[180:183], v[196:199], v[92:95]
	v_mfma_f32_16x16x32_bf16 v[84:87], v[172:175], v[204:207], v[84:87]
	v_mfma_f32_16x16x32_bf16 v[76:79], v[180:183], v[204:207], v[76:79]
	v_mfma_f32_16x16x32_bf16 v[68:71], v[172:175], v[222:225], v[68:71]
	v_mfma_f32_16x16x32_bf16 v[64:67], v[180:183], v[222:225], v[64:67]
	v_mfma_f32_16x16x32_bf16 v[116:119], v[176:179], v[192:195], v[116:119]
	v_mfma_f32_16x16x32_bf16 v[108:111], v[184:187], v[192:195], v[108:111]
	v_mfma_f32_16x16x32_bf16 v[100:103], v[176:179], v[200:203], v[100:103]
	v_mfma_f32_16x16x32_bf16 v[92:95], v[184:187], v[200:203], v[92:95]
	v_mfma_f32_16x16x32_bf16 v[84:87], v[176:179], v[218:221], v[84:87]
	v_mfma_f32_16x16x32_bf16 v[76:79], v[184:187], v[218:221], v[76:79]
	v_mfma_f32_16x16x32_bf16 v[68:71], v[176:179], v[226:229], v[68:71]
	v_mfma_f32_16x16x32_bf16 v[64:67], v[184:187], v[226:229], v[64:67]
	s_setprio 0
	s_barrier
	s_add_i32 s62, s85, s70
	v_lshl_add_u64 v[140:141], v[140:141], 0, s[0:1]
	s_mov_b32 m0, s62
	ds_read_b128 v[188:191], v144 offset:49152
	ds_read_b128 v[192:195], v144 offset:50176
	ds_read_b128 v[196:199], v144 offset:51200
	ds_read_b128 v[200:203], v144 offset:52224
	ds_read_b128 v[204:207], v144 offset:53248
	ds_read_b128 v[218:221], v144 offset:54272
	ds_read_b128 v[222:225], v144 offset:55296
	ds_read_b128 v[226:229], v144 offset:56320
	global_load_lds_dwordx4 v[140:141], off
	s_add_i32 m0, s62, 0x2000
	s_add_u32 s60, s60, 0x40080
	v_lshl_add_u64 v[140:141], v[146:147], 0, s[0:1]
	s_addc_u32 s61, s61, 0
	s_add_i32 s62, s88, s70
	global_load_lds_dwordx4 v[140:141], off
	v_lshl_add_u64 v[140:141], s[60:61], 0, v[148:149]
	s_mov_b32 m0, s62
	s_nop 0
	global_load_lds_dwordx4 v[140:141], off
	v_lshl_add_u64 v[140:141], s[60:61], 0, v[130:131]
	s_add_i32 m0, s62, 0x2000
	s_nop 0
	global_load_lds_dwordx4 v[140:141], off
	v_lshl_add_u64 v[140:141], v[208:209], 0, s[0:1]
	s_mov_b32 m0, s75
	s_nop 0
	global_load_lds_dwordx4 v[140:141], off
	v_lshl_add_u64 v[140:141], v[212:213], 0, s[0:1]
	s_mov_b32 m0, s76
	s_nop 0
	global_load_lds_dwordx4 v[140:141], off
	s_waitcnt vmcnt(8)
	s_waitcnt lgkmcnt(0)
	s_barrier
	s_setprio 1
	s_waitcnt lgkmcnt(0)
	v_mfma_f32_16x16x32_bf16 v[60:63], v[156:159], v[188:191], v[60:63]
	v_mfma_f32_16x16x32_bf16 v[56:59], v[164:167], v[188:191], v[56:59]
	v_mfma_f32_16x16x32_bf16 v[48:51], v[156:159], v[196:199], v[48:51]
	v_mfma_f32_16x16x32_bf16 v[40:43], v[164:167], v[196:199], v[40:43]
	v_mfma_f32_16x16x32_bf16 v[32:35], v[156:159], v[204:207], v[32:35]
	v_mfma_f32_16x16x32_bf16 v[24:27], v[164:167], v[204:207], v[24:27]
	v_mfma_f32_16x16x32_bf16 v[16:19], v[156:159], v[222:225], v[16:19]
	v_mfma_f32_16x16x32_bf16 v[8:11], v[164:167], v[222:225], v[8:11]
	v_mfma_f32_16x16x32_bf16 v[60:63], v[160:163], v[192:195], v[60:63]
	v_mfma_f32_16x16x32_bf16 v[56:59], v[168:171], v[192:195], v[56:59]
	v_mfma_f32_16x16x32_bf16 v[48:51], v[160:163], v[200:203], v[48:51]
	v_mfma_f32_16x16x32_bf16 v[40:43], v[168:171], v[200:203], v[40:43]
	v_mfma_f32_16x16x32_bf16 v[32:35], v[160:163], v[218:221], v[32:35]
	v_mfma_f32_16x16x32_bf16 v[24:27], v[168:171], v[218:221], v[24:27]
	v_mfma_f32_16x16x32_bf16 v[16:19], v[160:163], v[226:229], v[16:19]
	v_mfma_f32_16x16x32_bf16 v[8:11], v[168:171], v[226:229], v[8:11]
	s_setprio 0
	s_setprio 1
	v_mfma_f32_16x16x32_bf16 v[52:55], v[172:175], v[188:191], v[52:55]
	v_mfma_f32_16x16x32_bf16 v[44:47], v[180:183], v[188:191], v[44:47]
	v_mfma_f32_16x16x32_bf16 v[36:39], v[172:175], v[196:199], v[36:39]
	v_mfma_f32_16x16x32_bf16 v[28:31], v[180:183], v[196:199], v[28:31]
	v_mfma_f32_16x16x32_bf16 v[20:23], v[172:175], v[204:207], v[20:23]
	v_mfma_f32_16x16x32_bf16 v[12:15], v[180:183], v[204:207], v[12:15]
	v_mfma_f32_16x16x32_bf16 v[4:7], v[172:175], v[222:225], v[4:7]
	v_mfma_f32_16x16x32_bf16 v[0:3], v[180:183], v[222:225], v[0:3]
	v_mfma_f32_16x16x32_bf16 v[52:55], v[176:179], v[192:195], v[52:55]
	v_mfma_f32_16x16x32_bf16 v[44:47], v[184:187], v[192:195], v[44:47]
	v_mfma_f32_16x16x32_bf16 v[36:39], v[176:179], v[200:203], v[36:39]
	v_mfma_f32_16x16x32_bf16 v[28:31], v[184:187], v[200:203], v[28:31]
	v_mfma_f32_16x16x32_bf16 v[20:23], v[176:179], v[218:221], v[20:23]
	v_mfma_f32_16x16x32_bf16 v[12:15], v[184:187], v[218:221], v[12:15]
	v_mfma_f32_16x16x32_bf16 v[4:7], v[176:179], v[226:229], v[4:7]
	v_mfma_f32_16x16x32_bf16 v[0:3], v[184:187], v[226:229], v[0:3]
	s_setprio 0
	s_barrier
	s_add_i32 s84, s84, 2
	s_add_u32 s82, s82, 0x100
	s_addc_u32 s83, s83, 0
	s_add_u32 s58, s58, 0x100
	s_addc_u32 s59, s59, 0
	s_cmp_gt_u32 s84, 13
	s_cbranch_scc0 .LBB0_289
	s_and_b64 vcc, exec, s[38:39]
	s_cbranch_vccz .LBB0_292
	s_barrier
